# conv-A in P3 on waves 1,2,3,5 (wave 4 shares SIMD 0 with the S2 wave)
# baseline (speedup 1.0000x reference)
; __device__ __forceinline__ float bflo(unsigned w) { return __uint_as_float(w << 16); }
; __device__ __forceinline__ float bfhi(unsigned w) { return __uint_as_float(w & 0xffff0000u); }
; __device__ __forceinline__ float silu_f(float x) { return x * rcp_f(1.f + exp_f(-x)); }
; __device__ __forceinline__ u32x4 pack8(const float* v) { u32x4 o; o.x = pk2(v[0], v[1]); o.y = pk2(v[2], v[3]); o.z = pk2(v[4], v[5]); o.w = pk2(v[6], v[7]); return o; }
; __device__ __forceinline__ void conva_prompt(const bf16_t* z, const float* caw, bf16_t* ycat, int gt, int GT) {
; #pragma unroll 2
;     for (int idx = gt; idx < MP * 128; idx += GT) {
;         const int row = idx >> 7, c8 = (idx & 127) * 8, t = row & (SEQ - 1);
;         const bf16_t* zr = z + (size_t)row * NZ + c8;
;         float conv[8];
; #pragma unroll
;         for (int i = 0; i < 8; ++i) conv[i] = 0.f;
; #pragma unroll
;         for (int j = 0; j < 3; ++j) {
;             const bool ok = t - 2 + j >= 0; const ptrdiff_t ro = (ptrdiff_t)(ok ? j - 2 : 0) * NZ;
;             u32x4 c = *(const u32x4*)(zr + ro + 1024); const u32x4 hh = *(const u32x4*)(zr + ro + 2048);
;             if (!ok) c = (u32x4){0u, 0u, 0u, 0u};
;             const f32x4 w0 = *(const f32x4*)(caw + j * 1024 + c8), w1 = *(const f32x4*)(caw + j * 1024 + c8 + 4);
;             conv[0] += w0.x * (bflo(c.x) * bflo(hh.x)); conv[1] += w0.y * (bfhi(c.x) * bfhi(hh.x)); conv[2] += w0.z * (bflo(c.y) * bflo(hh.y)); conv[3] += w0.w * (bfhi(c.y) * bfhi(hh.y));
;             conv[4] += w1.x * (bflo(c.z) * bflo(hh.z)); conv[5] += w1.y * (bfhi(c.z) * bfhi(hh.z)); conv[6] += w1.z * (bflo(c.w) * bflo(hh.w)); conv[7] += w1.w * (bfhi(c.w) * bfhi(hh.w));
;         }
;         const u32x4 bb = *(const u32x4*)zr, gg = *(const u32x4*)(zr + 3072);
;         float y[8];
;         y[0] = bflo(bb.x) * conv[0] * silu_f(bflo(gg.x)); y[1] = bfhi(bb.x) * conv[1] * silu_f(bfhi(gg.x)); y[2] = bflo(bb.y) * conv[2] * silu_f(bflo(gg.y)); y[3] = bfhi(bb.y) * conv[3] * silu_f(bfhi(gg.y));
;         y[4] = bflo(bb.z) * conv[4] * silu_f(bflo(gg.z)); y[5] = bfhi(bb.z) * conv[5] * silu_f(bfhi(gg.z)); y[6] = bflo(bb.w) * conv[6] * silu_f(bflo(gg.w)); y[7] = bfhi(bb.w) * conv[7] * silu_f(bfhi(gg.w));
;         *(u32x4*)(ycat + (size_t)row * DM + c8) = pack8(y);
;     }
; }
.Lp3_conva:
	v_readfirstlane_b32 s14, v54
	s_lshr_b32 s14, s14, 6
	s_cmp_eq_u32 s14, 4
	s_cbranch_scc1 .LBB0_415
	s_cmp_gt_u32 s14, 5
	s_cbranch_scc1 .LBB0_415
	s_cmp_eq_u32 s14, 5
	s_cselect_b32 s23, 2, 1
	s_lshl_b32 s23, s23, 6
	s_load_dwordx2 s[4:5], s[0:1], 0x98
	s_load_dwordx2 s[8:9], s[0:1], 0x58
	s_mul_i32 s14, s92, 0x3000
	s_lshr_b32 s15, s49, 11
	s_lshl_b32 s15, s15, 8
	s_add_i32 s15, s15, s2
	s_lshl_b32 s15, s15, 10
	s_mov_b32 s10, 0xffff0000
	s_mov_b32 s11, 0xbfb8aa3b
	v_subrev_u32_e32 v33, s23, v54
	v_and_b32_e32 v32, 0x7f, v33
	v_lshlrev_b32_e32 v34, 5, v32
	v_lshlrev_b32_e32 v32, 4, v32
	v_add_u32_e32 v38, 0x1000, v34
	v_add_u32_e32 v39, 0x2000, v34
	v_add_u32_e32 v52, 0x1000, v32
	v_add_u32_e32 v33, s15, v33
	s_waitcnt lgkmcnt(0)
	s_add_u32 s6, s4, 0x20300000
	s_addc_u32 s7, s5, 0
	s_add_u32 s4, s4, 0x13c00000
	s_addc_u32 s5, s5, 0
	s_add_u32 s8, s8, s14
	s_addc_u32 s9, s9, 0
	global_load_dwordx4 v[8:11], v34, s[8:9]
	global_load_dwordx4 v[12:15], v34, s[8:9] offset:16
	global_load_dwordx4 v[16:19], v38, s[8:9]
	global_load_dwordx4 v[20:23], v38, s[8:9] offset:16
	global_load_dwordx4 v[24:27], v39, s[8:9]
	global_load_dwordx4 v[28:31], v39, s[8:9] offset:16
	v_lshrrev_b32_e32 v34, 7, v33
	v_and_b32_e32 v97, 0x7ff, v34
	v_lshl_add_u32 v35, v34, 14, v52
	v_min_u32_e32 v36, 2, v97
	v_min_u32_e32 v37, 1, v97
	v_lshlrev_b32_e32 v36, 14, v36
	v_lshlrev_b32_e32 v37, 14, v37
	v_sub_u32_e32 v36, v35, v36
	v_sub_u32_e32 v37, v35, v37
	v_lshl_add_u32 v96, v34, 12, v32
	global_load_dwordx4 v[64:67], v36, s[4:5] offset:-2048
	global_load_dwordx4 v[68:71], v36, s[4:5]
	global_load_dwordx4 v[72:75], v37, s[4:5] offset:-2048
	global_load_dwordx4 v[76:79], v37, s[4:5]
	global_load_dwordx4 v[80:83], v35, s[4:5] offset:-2048
	global_load_dwordx4 v[84:87], v35, s[4:5]
	global_load_dwordx4 v[88:91], v35, s[4:5] offset:-4096
	global_load_dwordx4 v[92:95], v35, s[4:5] offset:2048
	v_add_u32_e32 v33, 0x100, v33
	v_lshrrev_b32_e32 v34, 7, v33
	v_and_b32_e32 v133, 0x7ff, v34
	v_lshl_add_u32 v35, v34, 14, v52
	v_min_u32_e32 v36, 2, v133
	v_min_u32_e32 v37, 1, v133
	v_lshlrev_b32_e32 v36, 14, v36
	v_lshlrev_b32_e32 v37, 14, v37
	v_sub_u32_e32 v36, v35, v36
	v_sub_u32_e32 v37, v35, v37
	v_lshl_add_u32 v132, v34, 12, v32
	global_load_dwordx4 v[100:103], v36, s[4:5] offset:-2048
	global_load_dwordx4 v[104:107], v36, s[4:5]
	global_load_dwordx4 v[108:111], v37, s[4:5] offset:-2048
	global_load_dwordx4 v[112:115], v37, s[4:5]
	global_load_dwordx4 v[116:119], v35, s[4:5] offset:-2048
	global_load_dwordx4 v[120:123], v35, s[4:5]
	global_load_dwordx4 v[124:127], v35, s[4:5] offset:-4096
	global_load_dwordx4 v[128:131], v35, s[4:5] offset:2048
	v_add_u32_e32 v33, 0x100, v33
	v_lshrrev_b32_e32 v34, 7, v33
	v_and_b32_e32 v233, 0x7ff, v34
	v_lshl_add_u32 v35, v34, 14, v52
	v_min_u32_e32 v36, 2, v233
	v_min_u32_e32 v37, 1, v233
	v_lshlrev_b32_e32 v36, 14, v36
	v_lshlrev_b32_e32 v37, 14, v37
	v_sub_u32_e32 v36, v35, v36
	v_sub_u32_e32 v37, v35, v37
	v_lshl_add_u32 v232, v34, 12, v32
	global_load_dwordx4 v[200:203], v36, s[4:5] offset:-2048
	global_load_dwordx4 v[204:207], v36, s[4:5]
	global_load_dwordx4 v[208:211], v37, s[4:5] offset:-2048
	global_load_dwordx4 v[212:215], v37, s[4:5]
	global_load_dwordx4 v[216:219], v35, s[4:5] offset:-2048
	global_load_dwordx4 v[220:223], v35, s[4:5]
	global_load_dwordx4 v[224:227], v35, s[4:5] offset:-4096
	global_load_dwordx4 v[228:231], v35, s[4:5] offset:2048
	v_add_u32_e32 v33, 0x100, v33
	v_lshrrev_b32_e32 v34, 7, v33
	v_and_b32_e32 v189, 0x7ff, v34
	v_lshl_add_u32 v35, v34, 14, v52
	v_min_u32_e32 v36, 2, v189
	v_min_u32_e32 v37, 1, v189
	v_lshlrev_b32_e32 v36, 14, v36
	v_lshlrev_b32_e32 v37, 14, v37
	v_sub_u32_e32 v36, v35, v36
	v_sub_u32_e32 v37, v35, v37
	v_lshl_add_u32 v188, v34, 12, v32
	global_load_dwordx4 v[156:159], v36, s[4:5] offset:-2048
	global_load_dwordx4 v[160:163], v36, s[4:5]
	global_load_dwordx4 v[164:167], v37, s[4:5] offset:-2048
	global_load_dwordx4 v[168:171], v37, s[4:5]
	global_load_dwordx4 v[172:175], v35, s[4:5] offset:-2048
	global_load_dwordx4 v[176:179], v35, s[4:5]
	global_load_dwordx4 v[180:183], v35, s[4:5] offset:-4096
	global_load_dwordx4 v[184:187], v35, s[4:5] offset:2048
	v_add_u32_e32 v33, 0x100, v33
	s_waitcnt vmcnt(24)
; __device__ __forceinline__ float bflo(unsigned w) { return __uint_as_float(w << 16); }
; __device__ __forceinline__ float bfhi(unsigned w) { return __uint_as_float(w & 0xffff0000u); }
; __device__ __forceinline__ float silu_f(float x) { return x * rcp_f(1.f + exp_f(-x)); }
; __device__ __forceinline__ u32x4 pack8(const float* v) { u32x4 o; o.x = pk2(v[0], v[1]); o.y = pk2(v[2], v[3]); o.z = pk2(v[4], v[5]); o.w = pk2(v[6], v[7]); return o; }
; __device__ __forceinline__ void conva_prompt(const bf16_t* z, const float* caw, bf16_t* ycat, int gt, int GT) {
;     ...
;         for (int j = 0; j < 3; ++j) {
;             const bool ok = t - 2 + j >= 0; const ptrdiff_t ro = (ptrdiff_t)(ok ? j - 2 : 0) * NZ;
;             u32x4 c = *(const u32x4*)(zr + ro + 1024); const u32x4 hh = *(const u32x4*)(zr + ro + 2048);
;             if (!ok) c = (u32x4){0u, 0u, 0u, 0u};
;             const f32x4 w0 = *(const f32x4*)(caw + j * 1024 + c8), w1 = *(const f32x4*)(caw + j * 1024 + c8 + 4);
;             conv[0] += w0.x * (bflo(c.x) * bflo(hh.x)); conv[1] += w0.y * (bfhi(c.x) * bfhi(hh.x)); conv[2] += w0.z * (bflo(c.y) * bflo(hh.y)); conv[3] += w0.w * (bfhi(c.y) * bfhi(hh.y));
;             conv[4] += w1.x * (bflo(c.z) * bflo(hh.z)); conv[5] += w1.y * (bfhi(c.z) * bfhi(hh.z)); conv[6] += w1.z * (bflo(c.w) * bflo(hh.w)); conv[7] += w1.w * (bfhi(c.w) * bfhi(hh.w));
;         }
;         const u32x4 bb = *(const u32x4*)zr, gg = *(const u32x4*)(zr + 3072);
;         float y[8];
;         y[0] = bflo(bb.x) * conv[0] * silu_f(bflo(gg.x)); y[1] = bfhi(bb.x) * conv[1] * silu_f(bfhi(gg.x)); y[2] = bflo(bb.y) * conv[2] * silu_f(bflo(gg.y)); y[3] = bfhi(bb.y) * conv[3] * silu_f(bfhi(gg.y));
;         y[4] = bflo(bb.z) * conv[4] * silu_f(bflo(gg.z)); y[5] = bfhi(bb.z) * conv[5] * silu_f(bfhi(gg.z)); y[6] = bflo(bb.w) * conv[6] * silu_f(bflo(gg.w)); y[7] = bfhi(bb.w) * conv[7] * silu_f(bfhi(gg.w));
;         *(u32x4*)(ycat + (size_t)row * DM + c8) = pack8(y);
	v_cmp_lt_u32_e32 vcc, 1, v97
	v_lshlrev_b32_e32 v144, 16, v68
	v_and_b32_e32 v145, s10, v68
	v_lshlrev_b32_e32 v146, 16, v69
	v_and_b32_e32 v147, s10, v69
	v_lshlrev_b32_e32 v148, 16, v70
	v_and_b32_e32 v149, s10, v70
	v_lshlrev_b32_e32 v150, 16, v71
	v_and_b32_e32 v151, s10, v71
	v_cndmask_b32_e32 v64, 0, v64, vcc
	v_cndmask_b32_e32 v65, 0, v65, vcc
	v_cndmask_b32_e32 v66, 0, v66, vcc
	v_cndmask_b32_e32 v67, 0, v67, vcc
	v_cmp_ne_u32_e32 vcc, 0, v97
	v_lshlrev_b32_e32 v136, 16, v64
	v_and_b32_e32 v137, s10, v64
	v_lshlrev_b32_e32 v138, 16, v65
	v_and_b32_e32 v139, s10, v65
	v_lshlrev_b32_e32 v140, 16, v66
	v_and_b32_e32 v141, s10, v66
	v_lshlrev_b32_e32 v142, 16, v67
	v_and_b32_e32 v143, s10, v67
	v_cndmask_b32_e32 v72, 0, v72, vcc
	v_cndmask_b32_e32 v73, 0, v73, vcc
	v_cndmask_b32_e32 v74, 0, v74, vcc
	v_cndmask_b32_e32 v75, 0, v75, vcc
	v_pk_mul_f32 v[136:137], v[136:137], v[144:145]
	v_pk_mul_f32 v[138:139], v[138:139], v[146:147]
	v_pk_mul_f32 v[140:141], v[140:141], v[148:149]
	v_pk_mul_f32 v[142:143], v[142:143], v[150:151]
	v_pk_mul_f32 v[236:237], v[8:9], v[136:137]
	v_pk_mul_f32 v[238:239], v[10:11], v[138:139]
	v_pk_mul_f32 v[240:241], v[12:13], v[140:141]
	v_pk_mul_f32 v[242:243], v[14:15], v[142:143]
	v_lshlrev_b32_e32 v136, 16, v72
	v_and_b32_e32 v137, s10, v72
	v_lshlrev_b32_e32 v138, 16, v73
	v_and_b32_e32 v139, s10, v73
	v_lshlrev_b32_e32 v140, 16, v74
	v_and_b32_e32 v141, s10, v74
	v_lshlrev_b32_e32 v142, 16, v75
	v_and_b32_e32 v143, s10, v75
	v_lshlrev_b32_e32 v144, 16, v76
	v_and_b32_e32 v145, s10, v76
	v_lshlrev_b32_e32 v146, 16, v77
	v_and_b32_e32 v147, s10, v77
	v_lshlrev_b32_e32 v148, 16, v78
	v_and_b32_e32 v149, s10, v78
	v_lshlrev_b32_e32 v150, 16, v79
	v_and_b32_e32 v151, s10, v79
	v_pk_mul_f32 v[136:137], v[136:137], v[144:145]
	v_pk_mul_f32 v[138:139], v[138:139], v[146:147]
	v_pk_mul_f32 v[140:141], v[140:141], v[148:149]
	v_pk_mul_f32 v[142:143], v[142:143], v[150:151]
	v_pk_fma_f32 v[236:237], v[16:17], v[136:137], v[236:237]
	v_pk_fma_f32 v[238:239], v[18:19], v[138:139], v[238:239]
	v_pk_fma_f32 v[240:241], v[20:21], v[140:141], v[240:241]
	v_pk_fma_f32 v[242:243], v[22:23], v[142:143], v[242:243]
	v_lshlrev_b32_e32 v136, 16, v80
	v_and_b32_e32 v137, s10, v80
	v_lshlrev_b32_e32 v138, 16, v81
	v_and_b32_e32 v139, s10, v81
	v_lshlrev_b32_e32 v140, 16, v82
	v_and_b32_e32 v141, s10, v82
	v_lshlrev_b32_e32 v142, 16, v83
	v_and_b32_e32 v143, s10, v83
	v_lshlrev_b32_e32 v144, 16, v84
	v_and_b32_e32 v145, s10, v84
	v_lshlrev_b32_e32 v146, 16, v85
	v_and_b32_e32 v147, s10, v85
	v_lshlrev_b32_e32 v148, 16, v86
	v_and_b32_e32 v149, s10, v86
	v_lshlrev_b32_e32 v150, 16, v87
	v_and_b32_e32 v151, s10, v87
	v_pk_mul_f32 v[136:137], v[136:137], v[144:145]
	v_pk_mul_f32 v[138:139], v[138:139], v[146:147]
	v_pk_mul_f32 v[140:141], v[140:141], v[148:149]
	v_pk_mul_f32 v[142:143], v[142:143], v[150:151]
	v_pk_fma_f32 v[236:237], v[24:25], v[136:137], v[236:237]
	v_pk_fma_f32 v[238:239], v[26:27], v[138:139], v[238:239]
	v_pk_fma_f32 v[240:241], v[28:29], v[140:141], v[240:241]
	v_pk_fma_f32 v[242:243], v[30:31], v[142:143], v[242:243]
	v_lshlrev_b32_e32 v144, 16, v92
	v_and_b32_e32 v145, s10, v92
	v_lshlrev_b32_e32 v146, 16, v93
	v_and_b32_e32 v147, s10, v93
	v_lshlrev_b32_e32 v148, 16, v94
	v_and_b32_e32 v149, s10, v94
	v_lshlrev_b32_e32 v150, 16, v95
	v_and_b32_e32 v151, s10, v95
	v_mul_f32_e32 v136, s11, v144
	v_mul_f32_e32 v137, s11, v145
	v_mul_f32_e32 v138, s11, v146
	v_mul_f32_e32 v139, s11, v147
	v_mul_f32_e32 v140, s11, v148
	v_mul_f32_e32 v141, s11, v149
	v_mul_f32_e32 v142, s11, v150
	v_mul_f32_e32 v143, s11, v151
	v_exp_f32_e32 v136, v136
	v_exp_f32_e32 v137, v137
	v_exp_f32_e32 v138, v138
	v_exp_f32_e32 v139, v139
	v_exp_f32_e32 v140, v140
	v_exp_f32_e32 v141, v141
	v_exp_f32_e32 v142, v142
	v_exp_f32_e32 v143, v143
	v_lshlrev_b32_e32 v244, 16, v88
	v_and_b32_e32 v245, s10, v88
	v_lshlrev_b32_e32 v246, 16, v89
	v_and_b32_e32 v247, s10, v89
	v_lshlrev_b32_e32 v248, 16, v90
	v_and_b32_e32 v249, s10, v90
	v_lshlrev_b32_e32 v250, 16, v91
	v_and_b32_e32 v251, s10, v91
	v_add_f32_e32 v136, 1.0, v136
	v_add_f32_e32 v137, 1.0, v137
	v_add_f32_e32 v138, 1.0, v138
	v_add_f32_e32 v139, 1.0, v139
	v_add_f32_e32 v140, 1.0, v140
	v_add_f32_e32 v141, 1.0, v141
	v_add_f32_e32 v142, 1.0, v142
	v_add_f32_e32 v143, 1.0, v143
	v_rcp_f32_e32 v136, v136
	v_rcp_f32_e32 v137, v137
	v_rcp_f32_e32 v138, v138
	v_rcp_f32_e32 v139, v139
	v_rcp_f32_e32 v140, v140
	v_rcp_f32_e32 v141, v141
	v_rcp_f32_e32 v142, v142
	v_rcp_f32_e32 v143, v143
	v_pk_mul_f32 v[244:245], v[244:245], v[236:237]
	v_pk_mul_f32 v[246:247], v[246:247], v[238:239]
	v_pk_mul_f32 v[248:249], v[248:249], v[240:241]
	v_pk_mul_f32 v[250:251], v[250:251], v[242:243]
	v_pk_mul_f32 v[144:145], v[144:145], v[136:137]
	v_pk_mul_f32 v[146:147], v[146:147], v[138:139]
	v_pk_mul_f32 v[148:149], v[148:149], v[140:141]
	v_pk_mul_f32 v[150:151], v[150:151], v[142:143]
	v_pk_mul_f32 v[244:245], v[244:245], v[144:145]
	v_pk_mul_f32 v[246:247], v[246:247], v[146:147]
	v_pk_mul_f32 v[248:249], v[248:249], v[148:149]
	v_pk_mul_f32 v[250:251], v[250:251], v[150:151]
	v_cvt_pk_bf16_f32 v48, v244, v245
	v_cvt_pk_bf16_f32 v49, v246, v247
	v_cvt_pk_bf16_f32 v50, v248, v249
	v_cvt_pk_bf16_f32 v51, v250, v251
	global_store_dwordx4 v96, v[48:51], s[6:7]
	s_waitcnt vmcnt(17)
; __device__ __forceinline__ float bflo(unsigned w) { return __uint_as_float(w << 16); }
; __device__ __forceinline__ float bfhi(unsigned w) { return __uint_as_float(w & 0xffff0000u); }
; __device__ __forceinline__ float silu_f(float x) { return x * rcp_f(1.f + exp_f(-x)); }
; __device__ __forceinline__ u32x4 pack8(const float* v) { u32x4 o; o.x = pk2(v[0], v[1]); o.y = pk2(v[2], v[3]); o.z = pk2(v[4], v[5]); o.w = pk2(v[6], v[7]); return o; }
; __device__ __forceinline__ void conva_prompt(const bf16_t* z, const float* caw, bf16_t* ycat, int gt, int GT) {
;     ...
;         for (int j = 0; j < 3; ++j) {
;             const bool ok = t - 2 + j >= 0; const ptrdiff_t ro = (ptrdiff_t)(ok ? j - 2 : 0) * NZ;
;             u32x4 c = *(const u32x4*)(zr + ro + 1024); const u32x4 hh = *(const u32x4*)(zr + ro + 2048);
;             if (!ok) c = (u32x4){0u, 0u, 0u, 0u};
;             const f32x4 w0 = *(const f32x4*)(caw + j * 1024 + c8), w1 = *(const f32x4*)(caw + j * 1024 + c8 + 4);
;             conv[0] += w0.x * (bflo(c.x) * bflo(hh.x)); conv[1] += w0.y * (bfhi(c.x) * bfhi(hh.x)); conv[2] += w0.z * (bflo(c.y) * bflo(hh.y)); conv[3] += w0.w * (bfhi(c.y) * bfhi(hh.y));
;             conv[4] += w1.x * (bflo(c.z) * bflo(hh.z)); conv[5] += w1.y * (bfhi(c.z) * bfhi(hh.z)); conv[6] += w1.z * (bflo(c.w) * bflo(hh.w)); conv[7] += w1.w * (bfhi(c.w) * bfhi(hh.w));
;         }
;         const u32x4 bb = *(const u32x4*)zr, gg = *(const u32x4*)(zr + 3072);
;         float y[8];
;         y[0] = bflo(bb.x) * conv[0] * silu_f(bflo(gg.x)); y[1] = bfhi(bb.x) * conv[1] * silu_f(bfhi(gg.x)); y[2] = bflo(bb.y) * conv[2] * silu_f(bflo(gg.y)); y[3] = bfhi(bb.y) * conv[3] * silu_f(bfhi(gg.y));
;         y[4] = bflo(bb.z) * conv[4] * silu_f(bflo(gg.z)); y[5] = bfhi(bb.z) * conv[5] * silu_f(bfhi(gg.z)); y[6] = bflo(bb.w) * conv[6] * silu_f(bflo(gg.w)); y[7] = bfhi(bb.w) * conv[7] * silu_f(bfhi(gg.w));
;         *(u32x4*)(ycat + (size_t)row * DM + c8) = pack8(y);
	v_cmp_lt_u32_e32 vcc, 1, v133
	v_lshlrev_b32_e32 v144, 16, v104
	v_and_b32_e32 v145, s10, v104
	v_lshlrev_b32_e32 v146, 16, v105
	v_and_b32_e32 v147, s10, v105
	v_lshlrev_b32_e32 v148, 16, v106
	v_and_b32_e32 v149, s10, v106
	v_lshlrev_b32_e32 v150, 16, v107
	v_and_b32_e32 v151, s10, v107
	v_cndmask_b32_e32 v100, 0, v100, vcc
	v_cndmask_b32_e32 v101, 0, v101, vcc
	v_cndmask_b32_e32 v102, 0, v102, vcc
	v_cndmask_b32_e32 v103, 0, v103, vcc
	v_cmp_ne_u32_e32 vcc, 0, v133
	v_lshlrev_b32_e32 v136, 16, v100
	v_and_b32_e32 v137, s10, v100
	v_lshlrev_b32_e32 v138, 16, v101
	v_and_b32_e32 v139, s10, v101
	v_lshlrev_b32_e32 v140, 16, v102
	v_and_b32_e32 v141, s10, v102
	v_lshlrev_b32_e32 v142, 16, v103
	v_and_b32_e32 v143, s10, v103
	v_cndmask_b32_e32 v108, 0, v108, vcc
	v_cndmask_b32_e32 v109, 0, v109, vcc
	v_cndmask_b32_e32 v110, 0, v110, vcc
	v_cndmask_b32_e32 v111, 0, v111, vcc
	v_pk_mul_f32 v[136:137], v[136:137], v[144:145]
	v_pk_mul_f32 v[138:139], v[138:139], v[146:147]
	v_pk_mul_f32 v[140:141], v[140:141], v[148:149]
	v_pk_mul_f32 v[142:143], v[142:143], v[150:151]
	v_pk_mul_f32 v[236:237], v[8:9], v[136:137]
	v_pk_mul_f32 v[238:239], v[10:11], v[138:139]
	v_pk_mul_f32 v[240:241], v[12:13], v[140:141]
	v_pk_mul_f32 v[242:243], v[14:15], v[142:143]
	v_lshlrev_b32_e32 v136, 16, v108
	v_and_b32_e32 v137, s10, v108
	v_lshlrev_b32_e32 v138, 16, v109
	v_and_b32_e32 v139, s10, v109
	v_lshlrev_b32_e32 v140, 16, v110
	v_and_b32_e32 v141, s10, v110
	v_lshlrev_b32_e32 v142, 16, v111
	v_and_b32_e32 v143, s10, v111
	v_lshlrev_b32_e32 v144, 16, v112
	v_and_b32_e32 v145, s10, v112
	v_lshlrev_b32_e32 v146, 16, v113
	v_and_b32_e32 v147, s10, v113
	v_lshlrev_b32_e32 v148, 16, v114
	v_and_b32_e32 v149, s10, v114
	v_lshlrev_b32_e32 v150, 16, v115
	v_and_b32_e32 v151, s10, v115
	v_pk_mul_f32 v[136:137], v[136:137], v[144:145]
	v_pk_mul_f32 v[138:139], v[138:139], v[146:147]
	v_pk_mul_f32 v[140:141], v[140:141], v[148:149]
	v_pk_mul_f32 v[142:143], v[142:143], v[150:151]
	v_pk_fma_f32 v[236:237], v[16:17], v[136:137], v[236:237]
	v_pk_fma_f32 v[238:239], v[18:19], v[138:139], v[238:239]
	v_pk_fma_f32 v[240:241], v[20:21], v[140:141], v[240:241]
	v_pk_fma_f32 v[242:243], v[22:23], v[142:143], v[242:243]
	v_lshlrev_b32_e32 v136, 16, v116
	v_and_b32_e32 v137, s10, v116
	v_lshlrev_b32_e32 v138, 16, v117
	v_and_b32_e32 v139, s10, v117
	v_lshlrev_b32_e32 v140, 16, v118
	v_and_b32_e32 v141, s10, v118
	v_lshlrev_b32_e32 v142, 16, v119
	v_and_b32_e32 v143, s10, v119
	v_lshlrev_b32_e32 v144, 16, v120
	v_and_b32_e32 v145, s10, v120
	v_lshlrev_b32_e32 v146, 16, v121
	v_and_b32_e32 v147, s10, v121
	v_lshlrev_b32_e32 v148, 16, v122
	v_and_b32_e32 v149, s10, v122
	v_lshlrev_b32_e32 v150, 16, v123
	v_and_b32_e32 v151, s10, v123
	v_pk_mul_f32 v[136:137], v[136:137], v[144:145]
	v_pk_mul_f32 v[138:139], v[138:139], v[146:147]
	v_pk_mul_f32 v[140:141], v[140:141], v[148:149]
	v_pk_mul_f32 v[142:143], v[142:143], v[150:151]
	v_pk_fma_f32 v[236:237], v[24:25], v[136:137], v[236:237]
	v_pk_fma_f32 v[238:239], v[26:27], v[138:139], v[238:239]
	v_pk_fma_f32 v[240:241], v[28:29], v[140:141], v[240:241]
	v_pk_fma_f32 v[242:243], v[30:31], v[142:143], v[242:243]
	v_lshlrev_b32_e32 v144, 16, v128
	v_and_b32_e32 v145, s10, v128
	v_lshlrev_b32_e32 v146, 16, v129
	v_and_b32_e32 v147, s10, v129
	v_lshlrev_b32_e32 v148, 16, v130
	v_and_b32_e32 v149, s10, v130
	v_lshlrev_b32_e32 v150, 16, v131
	v_and_b32_e32 v151, s10, v131
	v_mul_f32_e32 v136, s11, v144
	v_mul_f32_e32 v137, s11, v145
	v_mul_f32_e32 v138, s11, v146
	v_mul_f32_e32 v139, s11, v147
	v_mul_f32_e32 v140, s11, v148
	v_mul_f32_e32 v141, s11, v149
	v_mul_f32_e32 v142, s11, v150
	v_mul_f32_e32 v143, s11, v151
	v_exp_f32_e32 v136, v136
	v_exp_f32_e32 v137, v137
	v_exp_f32_e32 v138, v138
	v_exp_f32_e32 v139, v139
	v_exp_f32_e32 v140, v140
	v_exp_f32_e32 v141, v141
	v_exp_f32_e32 v142, v142
	v_exp_f32_e32 v143, v143
	v_lshlrev_b32_e32 v244, 16, v124
	v_and_b32_e32 v245, s10, v124
	v_lshlrev_b32_e32 v246, 16, v125
	v_and_b32_e32 v247, s10, v125
	v_lshlrev_b32_e32 v248, 16, v126
	v_and_b32_e32 v249, s10, v126
	v_lshlrev_b32_e32 v250, 16, v127
	v_and_b32_e32 v251, s10, v127
	v_add_f32_e32 v136, 1.0, v136
	v_add_f32_e32 v137, 1.0, v137
	v_add_f32_e32 v138, 1.0, v138
	v_add_f32_e32 v139, 1.0, v139
	v_add_f32_e32 v140, 1.0, v140
	v_add_f32_e32 v141, 1.0, v141
	v_add_f32_e32 v142, 1.0, v142
	v_add_f32_e32 v143, 1.0, v143
	v_rcp_f32_e32 v136, v136
	v_rcp_f32_e32 v137, v137
	v_rcp_f32_e32 v138, v138
	v_rcp_f32_e32 v139, v139
	v_rcp_f32_e32 v140, v140
	v_rcp_f32_e32 v141, v141
	v_rcp_f32_e32 v142, v142
	v_rcp_f32_e32 v143, v143
	v_pk_mul_f32 v[244:245], v[244:245], v[236:237]
	v_pk_mul_f32 v[246:247], v[246:247], v[238:239]
	v_pk_mul_f32 v[248:249], v[248:249], v[240:241]
	v_pk_mul_f32 v[250:251], v[250:251], v[242:243]
	v_pk_mul_f32 v[144:145], v[144:145], v[136:137]
	v_pk_mul_f32 v[146:147], v[146:147], v[138:139]
	v_pk_mul_f32 v[148:149], v[148:149], v[140:141]
	v_pk_mul_f32 v[150:151], v[150:151], v[142:143]
	v_pk_mul_f32 v[244:245], v[244:245], v[144:145]
	v_pk_mul_f32 v[246:247], v[246:247], v[146:147]
	v_pk_mul_f32 v[248:249], v[248:249], v[148:149]
	v_pk_mul_f32 v[250:251], v[250:251], v[150:151]
	v_cvt_pk_bf16_f32 v48, v244, v245
	v_cvt_pk_bf16_f32 v49, v246, v247
	v_cvt_pk_bf16_f32 v50, v248, v249
	v_cvt_pk_bf16_f32 v51, v250, v251
	global_store_dwordx4 v132, v[48:51], s[6:7]
	s_waitcnt vmcnt(10)
; __device__ __forceinline__ float bflo(unsigned w) { return __uint_as_float(w << 16); }
; __device__ __forceinline__ float bfhi(unsigned w) { return __uint_as_float(w & 0xffff0000u); }
; __device__ __forceinline__ float silu_f(float x) { return x * rcp_f(1.f + exp_f(-x)); }
; __device__ __forceinline__ u32x4 pack8(const float* v) { u32x4 o; o.x = pk2(v[0], v[1]); o.y = pk2(v[2], v[3]); o.z = pk2(v[4], v[5]); o.w = pk2(v[6], v[7]); return o; }
; __device__ __forceinline__ void conva_prompt(const bf16_t* z, const float* caw, bf16_t* ycat, int gt, int GT) {
;     ...
;         for (int j = 0; j < 3; ++j) {
;             const bool ok = t - 2 + j >= 0; const ptrdiff_t ro = (ptrdiff_t)(ok ? j - 2 : 0) * NZ;
;             u32x4 c = *(const u32x4*)(zr + ro + 1024); const u32x4 hh = *(const u32x4*)(zr + ro + 2048);
;             if (!ok) c = (u32x4){0u, 0u, 0u, 0u};
;             const f32x4 w0 = *(const f32x4*)(caw + j * 1024 + c8), w1 = *(const f32x4*)(caw + j * 1024 + c8 + 4);
;             conv[0] += w0.x * (bflo(c.x) * bflo(hh.x)); conv[1] += w0.y * (bfhi(c.x) * bfhi(hh.x)); conv[2] += w0.z * (bflo(c.y) * bflo(hh.y)); conv[3] += w0.w * (bfhi(c.y) * bfhi(hh.y));
;             conv[4] += w1.x * (bflo(c.z) * bflo(hh.z)); conv[5] += w1.y * (bfhi(c.z) * bfhi(hh.z)); conv[6] += w1.z * (bflo(c.w) * bflo(hh.w)); conv[7] += w1.w * (bfhi(c.w) * bfhi(hh.w));
;         }
;         const u32x4 bb = *(const u32x4*)zr, gg = *(const u32x4*)(zr + 3072);
;         float y[8];
;         y[0] = bflo(bb.x) * conv[0] * silu_f(bflo(gg.x)); y[1] = bfhi(bb.x) * conv[1] * silu_f(bfhi(gg.x)); y[2] = bflo(bb.y) * conv[2] * silu_f(bflo(gg.y)); y[3] = bfhi(bb.y) * conv[3] * silu_f(bfhi(gg.y));
;         y[4] = bflo(bb.z) * conv[4] * silu_f(bflo(gg.z)); y[5] = bfhi(bb.z) * conv[5] * silu_f(bfhi(gg.z)); y[6] = bflo(bb.w) * conv[6] * silu_f(bflo(gg.w)); y[7] = bfhi(bb.w) * conv[7] * silu_f(bfhi(gg.w));
;         *(u32x4*)(ycat + (size_t)row * DM + c8) = pack8(y);
	v_cmp_lt_u32_e32 vcc, 1, v233
	v_lshlrev_b32_e32 v144, 16, v204
	v_and_b32_e32 v145, s10, v204
	v_lshlrev_b32_e32 v146, 16, v205
	v_and_b32_e32 v147, s10, v205
	v_lshlrev_b32_e32 v148, 16, v206
	v_and_b32_e32 v149, s10, v206
	v_lshlrev_b32_e32 v150, 16, v207
	v_and_b32_e32 v151, s10, v207
	v_cndmask_b32_e32 v200, 0, v200, vcc
	v_cndmask_b32_e32 v201, 0, v201, vcc
	v_cndmask_b32_e32 v202, 0, v202, vcc
	v_cndmask_b32_e32 v203, 0, v203, vcc
	v_cmp_ne_u32_e32 vcc, 0, v233
	v_lshlrev_b32_e32 v136, 16, v200
	v_and_b32_e32 v137, s10, v200
	v_lshlrev_b32_e32 v138, 16, v201
	v_and_b32_e32 v139, s10, v201
	v_lshlrev_b32_e32 v140, 16, v202
	v_and_b32_e32 v141, s10, v202
	v_lshlrev_b32_e32 v142, 16, v203
	v_and_b32_e32 v143, s10, v203
	v_cndmask_b32_e32 v208, 0, v208, vcc
	v_cndmask_b32_e32 v209, 0, v209, vcc
	v_cndmask_b32_e32 v210, 0, v210, vcc
	v_cndmask_b32_e32 v211, 0, v211, vcc
	v_pk_mul_f32 v[136:137], v[136:137], v[144:145]
	v_pk_mul_f32 v[138:139], v[138:139], v[146:147]
	v_pk_mul_f32 v[140:141], v[140:141], v[148:149]
	v_pk_mul_f32 v[142:143], v[142:143], v[150:151]
	v_pk_mul_f32 v[236:237], v[8:9], v[136:137]
	v_pk_mul_f32 v[238:239], v[10:11], v[138:139]
	v_pk_mul_f32 v[240:241], v[12:13], v[140:141]
	v_pk_mul_f32 v[242:243], v[14:15], v[142:143]
	v_lshlrev_b32_e32 v136, 16, v208
	v_and_b32_e32 v137, s10, v208
	v_lshlrev_b32_e32 v138, 16, v209
	v_and_b32_e32 v139, s10, v209
	v_lshlrev_b32_e32 v140, 16, v210
	v_and_b32_e32 v141, s10, v210
	v_lshlrev_b32_e32 v142, 16, v211
	v_and_b32_e32 v143, s10, v211
	v_lshlrev_b32_e32 v144, 16, v212
	v_and_b32_e32 v145, s10, v212
	v_lshlrev_b32_e32 v146, 16, v213
	v_and_b32_e32 v147, s10, v213
	v_lshlrev_b32_e32 v148, 16, v214
	v_and_b32_e32 v149, s10, v214
	v_lshlrev_b32_e32 v150, 16, v215
	v_and_b32_e32 v151, s10, v215
	v_pk_mul_f32 v[136:137], v[136:137], v[144:145]
	v_pk_mul_f32 v[138:139], v[138:139], v[146:147]
	v_pk_mul_f32 v[140:141], v[140:141], v[148:149]
	v_pk_mul_f32 v[142:143], v[142:143], v[150:151]
	v_pk_fma_f32 v[236:237], v[16:17], v[136:137], v[236:237]
	v_pk_fma_f32 v[238:239], v[18:19], v[138:139], v[238:239]
	v_pk_fma_f32 v[240:241], v[20:21], v[140:141], v[240:241]
	v_pk_fma_f32 v[242:243], v[22:23], v[142:143], v[242:243]
	v_lshlrev_b32_e32 v136, 16, v216
	v_and_b32_e32 v137, s10, v216
	v_lshlrev_b32_e32 v138, 16, v217
	v_and_b32_e32 v139, s10, v217
	v_lshlrev_b32_e32 v140, 16, v218
	v_and_b32_e32 v141, s10, v218
	v_lshlrev_b32_e32 v142, 16, v219
	v_and_b32_e32 v143, s10, v219
	v_lshlrev_b32_e32 v144, 16, v220
	v_and_b32_e32 v145, s10, v220
	v_lshlrev_b32_e32 v146, 16, v221
	v_and_b32_e32 v147, s10, v221
	v_lshlrev_b32_e32 v148, 16, v222
	v_and_b32_e32 v149, s10, v222
	v_lshlrev_b32_e32 v150, 16, v223
	v_and_b32_e32 v151, s10, v223
	v_pk_mul_f32 v[136:137], v[136:137], v[144:145]
	v_pk_mul_f32 v[138:139], v[138:139], v[146:147]
	v_pk_mul_f32 v[140:141], v[140:141], v[148:149]
	v_pk_mul_f32 v[142:143], v[142:143], v[150:151]
	v_pk_fma_f32 v[236:237], v[24:25], v[136:137], v[236:237]
	v_pk_fma_f32 v[238:239], v[26:27], v[138:139], v[238:239]
	v_pk_fma_f32 v[240:241], v[28:29], v[140:141], v[240:241]
	v_pk_fma_f32 v[242:243], v[30:31], v[142:143], v[242:243]
	v_lshlrev_b32_e32 v144, 16, v228
	v_and_b32_e32 v145, s10, v228
	v_lshlrev_b32_e32 v146, 16, v229
	v_and_b32_e32 v147, s10, v229
	v_lshlrev_b32_e32 v148, 16, v230
	v_and_b32_e32 v149, s10, v230
	v_lshlrev_b32_e32 v150, 16, v231
	v_and_b32_e32 v151, s10, v231
	v_mul_f32_e32 v136, s11, v144
	v_mul_f32_e32 v137, s11, v145
	v_mul_f32_e32 v138, s11, v146
	v_mul_f32_e32 v139, s11, v147
	v_mul_f32_e32 v140, s11, v148
	v_mul_f32_e32 v141, s11, v149
	v_mul_f32_e32 v142, s11, v150
	v_mul_f32_e32 v143, s11, v151
	v_exp_f32_e32 v136, v136
	v_exp_f32_e32 v137, v137
	v_exp_f32_e32 v138, v138
	v_exp_f32_e32 v139, v139
	v_exp_f32_e32 v140, v140
	v_exp_f32_e32 v141, v141
	v_exp_f32_e32 v142, v142
	v_exp_f32_e32 v143, v143
	v_lshlrev_b32_e32 v244, 16, v224
	v_and_b32_e32 v245, s10, v224
	v_lshlrev_b32_e32 v246, 16, v225
	v_and_b32_e32 v247, s10, v225
	v_lshlrev_b32_e32 v248, 16, v226
	v_and_b32_e32 v249, s10, v226
	v_lshlrev_b32_e32 v250, 16, v227
	v_and_b32_e32 v251, s10, v227
	v_add_f32_e32 v136, 1.0, v136
	v_add_f32_e32 v137, 1.0, v137
	v_add_f32_e32 v138, 1.0, v138
	v_add_f32_e32 v139, 1.0, v139
	v_add_f32_e32 v140, 1.0, v140
	v_add_f32_e32 v141, 1.0, v141
	v_add_f32_e32 v142, 1.0, v142
	v_add_f32_e32 v143, 1.0, v143
	v_rcp_f32_e32 v136, v136
	v_rcp_f32_e32 v137, v137
	v_rcp_f32_e32 v138, v138
	v_rcp_f32_e32 v139, v139
	v_rcp_f32_e32 v140, v140
	v_rcp_f32_e32 v141, v141
	v_rcp_f32_e32 v142, v142
	v_rcp_f32_e32 v143, v143
	v_pk_mul_f32 v[244:245], v[244:245], v[236:237]
	v_pk_mul_f32 v[246:247], v[246:247], v[238:239]
	v_pk_mul_f32 v[248:249], v[248:249], v[240:241]
	v_pk_mul_f32 v[250:251], v[250:251], v[242:243]
	v_pk_mul_f32 v[144:145], v[144:145], v[136:137]
	v_pk_mul_f32 v[146:147], v[146:147], v[138:139]
	v_pk_mul_f32 v[148:149], v[148:149], v[140:141]
	v_pk_mul_f32 v[150:151], v[150:151], v[142:143]
	v_pk_mul_f32 v[244:245], v[244:245], v[144:145]
	v_pk_mul_f32 v[246:247], v[246:247], v[146:147]
	v_pk_mul_f32 v[248:249], v[248:249], v[148:149]
	v_pk_mul_f32 v[250:251], v[250:251], v[150:151]
	v_cvt_pk_bf16_f32 v48, v244, v245
	v_cvt_pk_bf16_f32 v49, v246, v247
	v_cvt_pk_bf16_f32 v50, v248, v249
	v_cvt_pk_bf16_f32 v51, v250, v251
	global_store_dwordx4 v232, v[48:51], s[6:7]
	s_waitcnt vmcnt(3)
; __device__ __forceinline__ float bflo(unsigned w) { return __uint_as_float(w << 16); }
; __device__ __forceinline__ float bfhi(unsigned w) { return __uint_as_float(w & 0xffff0000u); }
; __device__ __forceinline__ float silu_f(float x) { return x * rcp_f(1.f + exp_f(-x)); }
; __device__ __forceinline__ u32x4 pack8(const float* v) { u32x4 o; o.x = pk2(v[0], v[1]); o.y = pk2(v[2], v[3]); o.z = pk2(v[4], v[5]); o.w = pk2(v[6], v[7]); return o; }
; __device__ __forceinline__ void conva_prompt(const bf16_t* z, const float* caw, bf16_t* ycat, int gt, int GT) {
;     ...
;         for (int j = 0; j < 3; ++j) {
;             const bool ok = t - 2 + j >= 0; const ptrdiff_t ro = (ptrdiff_t)(ok ? j - 2 : 0) * NZ;
;             u32x4 c = *(const u32x4*)(zr + ro + 1024); const u32x4 hh = *(const u32x4*)(zr + ro + 2048);
;             if (!ok) c = (u32x4){0u, 0u, 0u, 0u};
;             const f32x4 w0 = *(const f32x4*)(caw + j * 1024 + c8), w1 = *(const f32x4*)(caw + j * 1024 + c8 + 4);
;             conv[0] += w0.x * (bflo(c.x) * bflo(hh.x)); conv[1] += w0.y * (bfhi(c.x) * bfhi(hh.x)); conv[2] += w0.z * (bflo(c.y) * bflo(hh.y)); conv[3] += w0.w * (bfhi(c.y) * bfhi(hh.y));
;             conv[4] += w1.x * (bflo(c.z) * bflo(hh.z)); conv[5] += w1.y * (bfhi(c.z) * bfhi(hh.z)); conv[6] += w1.z * (bflo(c.w) * bflo(hh.w)); conv[7] += w1.w * (bfhi(c.w) * bfhi(hh.w));
;         }
;         const u32x4 bb = *(const u32x4*)zr, gg = *(const u32x4*)(zr + 3072);
;         float y[8];
;         y[0] = bflo(bb.x) * conv[0] * silu_f(bflo(gg.x)); y[1] = bfhi(bb.x) * conv[1] * silu_f(bfhi(gg.x)); y[2] = bflo(bb.y) * conv[2] * silu_f(bflo(gg.y)); y[3] = bfhi(bb.y) * conv[3] * silu_f(bfhi(gg.y));
;         y[4] = bflo(bb.z) * conv[4] * silu_f(bflo(gg.z)); y[5] = bfhi(bb.z) * conv[5] * silu_f(bfhi(gg.z)); y[6] = bflo(bb.w) * conv[6] * silu_f(bflo(gg.w)); y[7] = bfhi(bb.w) * conv[7] * silu_f(bfhi(gg.w));
;         *(u32x4*)(ycat + (size_t)row * DM + c8) = pack8(y);
	v_cmp_lt_u32_e32 vcc, 1, v189
	v_lshlrev_b32_e32 v144, 16, v160
	v_and_b32_e32 v145, s10, v160
	v_lshlrev_b32_e32 v146, 16, v161
	v_and_b32_e32 v147, s10, v161
	v_lshlrev_b32_e32 v148, 16, v162
	v_and_b32_e32 v149, s10, v162
	v_lshlrev_b32_e32 v150, 16, v163
	v_and_b32_e32 v151, s10, v163
	v_cndmask_b32_e32 v156, 0, v156, vcc
	v_cndmask_b32_e32 v157, 0, v157, vcc
	v_cndmask_b32_e32 v158, 0, v158, vcc
	v_cndmask_b32_e32 v159, 0, v159, vcc
	v_cmp_ne_u32_e32 vcc, 0, v189
	v_lshlrev_b32_e32 v136, 16, v156
	v_and_b32_e32 v137, s10, v156
	v_lshlrev_b32_e32 v138, 16, v157
	v_and_b32_e32 v139, s10, v157
	v_lshlrev_b32_e32 v140, 16, v158
	v_and_b32_e32 v141, s10, v158
	v_lshlrev_b32_e32 v142, 16, v159
	v_and_b32_e32 v143, s10, v159
	v_cndmask_b32_e32 v164, 0, v164, vcc
	v_cndmask_b32_e32 v165, 0, v165, vcc
	v_cndmask_b32_e32 v166, 0, v166, vcc
	v_cndmask_b32_e32 v167, 0, v167, vcc
	v_pk_mul_f32 v[136:137], v[136:137], v[144:145]
	v_pk_mul_f32 v[138:139], v[138:139], v[146:147]
	v_pk_mul_f32 v[140:141], v[140:141], v[148:149]
	v_pk_mul_f32 v[142:143], v[142:143], v[150:151]
	v_pk_mul_f32 v[236:237], v[8:9], v[136:137]
	v_pk_mul_f32 v[238:239], v[10:11], v[138:139]
	v_pk_mul_f32 v[240:241], v[12:13], v[140:141]
	v_pk_mul_f32 v[242:243], v[14:15], v[142:143]
	v_lshlrev_b32_e32 v136, 16, v164
	v_and_b32_e32 v137, s10, v164
	v_lshlrev_b32_e32 v138, 16, v165
	v_and_b32_e32 v139, s10, v165
	v_lshlrev_b32_e32 v140, 16, v166
	v_and_b32_e32 v141, s10, v166
	v_lshlrev_b32_e32 v142, 16, v167
	v_and_b32_e32 v143, s10, v167
	v_lshlrev_b32_e32 v144, 16, v168
	v_and_b32_e32 v145, s10, v168
	v_lshlrev_b32_e32 v146, 16, v169
	v_and_b32_e32 v147, s10, v169
	v_lshlrev_b32_e32 v148, 16, v170
	v_and_b32_e32 v149, s10, v170
	v_lshlrev_b32_e32 v150, 16, v171
	v_and_b32_e32 v151, s10, v171
	v_pk_mul_f32 v[136:137], v[136:137], v[144:145]
	v_pk_mul_f32 v[138:139], v[138:139], v[146:147]
	v_pk_mul_f32 v[140:141], v[140:141], v[148:149]
	v_pk_mul_f32 v[142:143], v[142:143], v[150:151]
	v_pk_fma_f32 v[236:237], v[16:17], v[136:137], v[236:237]
	v_pk_fma_f32 v[238:239], v[18:19], v[138:139], v[238:239]
	v_pk_fma_f32 v[240:241], v[20:21], v[140:141], v[240:241]
	v_pk_fma_f32 v[242:243], v[22:23], v[142:143], v[242:243]
	v_lshlrev_b32_e32 v136, 16, v172
	v_and_b32_e32 v137, s10, v172
	v_lshlrev_b32_e32 v138, 16, v173
	v_and_b32_e32 v139, s10, v173
	v_lshlrev_b32_e32 v140, 16, v174
	v_and_b32_e32 v141, s10, v174
	v_lshlrev_b32_e32 v142, 16, v175
	v_and_b32_e32 v143, s10, v175
	v_lshlrev_b32_e32 v144, 16, v176
	v_and_b32_e32 v145, s10, v176
	v_lshlrev_b32_e32 v146, 16, v177
	v_and_b32_e32 v147, s10, v177
	v_lshlrev_b32_e32 v148, 16, v178
	v_and_b32_e32 v149, s10, v178
	v_lshlrev_b32_e32 v150, 16, v179
	v_and_b32_e32 v151, s10, v179
	v_pk_mul_f32 v[136:137], v[136:137], v[144:145]
	v_pk_mul_f32 v[138:139], v[138:139], v[146:147]
	v_pk_mul_f32 v[140:141], v[140:141], v[148:149]
	v_pk_mul_f32 v[142:143], v[142:143], v[150:151]
	v_pk_fma_f32 v[236:237], v[24:25], v[136:137], v[236:237]
	v_pk_fma_f32 v[238:239], v[26:27], v[138:139], v[238:239]
	v_pk_fma_f32 v[240:241], v[28:29], v[140:141], v[240:241]
	v_pk_fma_f32 v[242:243], v[30:31], v[142:143], v[242:243]
	v_lshlrev_b32_e32 v144, 16, v184
	v_and_b32_e32 v145, s10, v184
	v_lshlrev_b32_e32 v146, 16, v185
	v_and_b32_e32 v147, s10, v185
	v_lshlrev_b32_e32 v148, 16, v186
	v_and_b32_e32 v149, s10, v186
	v_lshlrev_b32_e32 v150, 16, v187
	v_and_b32_e32 v151, s10, v187
	v_mul_f32_e32 v136, s11, v144
	v_mul_f32_e32 v137, s11, v145
	v_mul_f32_e32 v138, s11, v146
	v_mul_f32_e32 v139, s11, v147
	v_mul_f32_e32 v140, s11, v148
	v_mul_f32_e32 v141, s11, v149
	v_mul_f32_e32 v142, s11, v150
	v_mul_f32_e32 v143, s11, v151
	v_exp_f32_e32 v136, v136
	v_exp_f32_e32 v137, v137
	v_exp_f32_e32 v138, v138
	v_exp_f32_e32 v139, v139
	v_exp_f32_e32 v140, v140
	v_exp_f32_e32 v141, v141
	v_exp_f32_e32 v142, v142
	v_exp_f32_e32 v143, v143
	v_lshlrev_b32_e32 v244, 16, v180
	v_and_b32_e32 v245, s10, v180
	v_lshlrev_b32_e32 v246, 16, v181
	v_and_b32_e32 v247, s10, v181
	v_lshlrev_b32_e32 v248, 16, v182
	v_and_b32_e32 v249, s10, v182
	v_lshlrev_b32_e32 v250, 16, v183
	v_and_b32_e32 v251, s10, v183
	v_add_f32_e32 v136, 1.0, v136
	v_add_f32_e32 v137, 1.0, v137
	v_add_f32_e32 v138, 1.0, v138
	v_add_f32_e32 v139, 1.0, v139
	v_add_f32_e32 v140, 1.0, v140
	v_add_f32_e32 v141, 1.0, v141
	v_add_f32_e32 v142, 1.0, v142
	v_add_f32_e32 v143, 1.0, v143
	v_rcp_f32_e32 v136, v136
	v_rcp_f32_e32 v137, v137
	v_rcp_f32_e32 v138, v138
	v_rcp_f32_e32 v139, v139
	v_rcp_f32_e32 v140, v140
	v_rcp_f32_e32 v141, v141
	v_rcp_f32_e32 v142, v142
	v_rcp_f32_e32 v143, v143
	v_pk_mul_f32 v[244:245], v[244:245], v[236:237]
	v_pk_mul_f32 v[246:247], v[246:247], v[238:239]
	v_pk_mul_f32 v[248:249], v[248:249], v[240:241]
	v_pk_mul_f32 v[250:251], v[250:251], v[242:243]
	v_pk_mul_f32 v[144:145], v[144:145], v[136:137]
	v_pk_mul_f32 v[146:147], v[146:147], v[138:139]
	v_pk_mul_f32 v[148:149], v[148:149], v[140:141]
	v_pk_mul_f32 v[150:151], v[150:151], v[142:143]
	v_pk_mul_f32 v[244:245], v[244:245], v[144:145]
	v_pk_mul_f32 v[246:247], v[246:247], v[146:147]
	v_pk_mul_f32 v[248:249], v[248:249], v[148:149]
	v_pk_mul_f32 v[250:251], v[250:251], v[150:151]
	v_cvt_pk_bf16_f32 v48, v244, v245
	v_cvt_pk_bf16_f32 v49, v246, v247
	v_cvt_pk_bf16_f32 v50, v248, v249
	v_cvt_pk_bf16_f32 v51, v250, v251
	global_store_dwordx4 v188, v[48:51], s[6:7]
	s_branch .LBB0_415
